# phase_final: hand-written path with g held in registers and double-buffered row loads
# baseline (speedup 1.0000x reference)
; __device__ __forceinline__ KP kp_launder(KP k) { unsigned z; asm volatile("s_mov_b32 %0, 0" : "=s"(z)); return (KP)((const __attribute__((address_space(4))) char*)__builtin_amdgcn_kernarg_segment_ptr() + z); }
; __device__ __forceinline__ int tidx() { int t = threadIdx.x; asm volatile("" : "+v"(t)); return t; }
; __device__ __forceinline__ int bidx() { int t = blockIdx.x; asm volatile("" : "+s"(t)); return t; }
; #define FIN_LOAD(V, R_) { const float* s = p->out + (size_t)(R_) * DM; UFOR(j, 8) V[j] = *(const float4*)(s + j * 256 + lane * 4); }
; __device__ __forceinline__ void phase_final(KP p) {
;   const int tid_ = tidx(); const int bid_ = bidx(); (void)bid_;
;   p = kp_launder(p);
;   const float* g = p->in[26];
;   const int lane = tid_ & 63, wv = tid_ >> 6;
;   const int stride = gridDim.x * 8;
;   float4 va[8], vb[8];
;     ...
;   int r = bid_ * 8 + wv;
;   if (r < ML) FIN_LOAD(va, r);
;   for (; r < ML; r += 2 * stride) {
;     if (r + stride < ML) FIN_LOAD(vb, r + stride);
;     FIN_BODY(va, r);
;     if (r + 2 * stride < ML) FIN_LOAD(va, r + 2 * stride);
;     if (r + stride < ML) FIN_BODY(vb, r + stride);
;   }
.LBB0_1255:
	s_cmp_gt_i32 s68, 23
	s_cselect_b64 s[2:3], -1, 0
	s_cmp_lt_i32 s68, 24
	s_cselect_b64 s[6:7], -1, 0
	s_cmp_gt_i32 s69, 23
	s_cselect_b64 s[4:5], -1, 0
	s_and_b64 s[4:5], s[4:5], s[6:7]
	s_and_b64 vcc, exec, s[4:5]
	s_cbranch_vccz .LBB0_1266
	s_load_dwordx2 s[40:41], s[0:1], 0xd8
	s_load_dwordx2 s[48:49], s[0:1], 0xd0
	v_and_b32_e32 v128, 63, v135
	v_lshlrev_b32_e32 v129, 4, v128
	v_add_u32_e32 v130, 0x1000, v129
	v_lshrrev_b32_e32 v131, 6, v135
	s_lshl_b32 s19, s78, 3
	v_add_u32_e32 v131, s19, v131
	v_lshl_add_u32 v136, v131, 13, v129
	v_add_u32_e32 v137, 0x1000, v136
	v_mov_b32_e32 v132, v136
	v_mov_b32_e32 v134, v137
	s_waitcnt lgkmcnt(0)
	global_load_dwordx4 v[0:3], v129, s[48:49]
	global_load_dwordx4 v[4:7], v129, s[48:49] offset:1024
	global_load_dwordx4 v[8:11], v129, s[48:49] offset:2048
	global_load_dwordx4 v[12:15], v129, s[48:49] offset:3072
	global_load_dwordx4 v[16:19], v130, s[48:49]
	global_load_dwordx4 v[20:23], v130, s[48:49] offset:1024
	global_load_dwordx4 v[24:27], v130, s[48:49] offset:2048
	global_load_dwordx4 v[28:31], v130, s[48:49] offset:3072
	global_load_dwordx4 v[96:99], v136, s[40:41]
	global_load_dwordx4 v[100:103], v136, s[40:41] offset:1024
	global_load_dwordx4 v[104:107], v136, s[40:41] offset:2048
	global_load_dwordx4 v[108:111], v136, s[40:41] offset:3072
	global_load_dwordx4 v[112:115], v137, s[40:41]
	global_load_dwordx4 v[116:119], v137, s[40:41] offset:1024
	global_load_dwordx4 v[120:123], v137, s[40:41] offset:2048
	global_load_dwordx4 v[124:127], v137, s[40:41] offset:3072
	s_mov_b32 s7, 0
.Lfinal_block:
	v_add_u32_e32 v136, 0x1000000, v136
	v_add_u32_e32 v137, 0x1000000, v137
	global_load_dwordx4 v[140:143], v136, s[40:41]
	global_load_dwordx4 v[144:147], v136, s[40:41] offset:1024
	global_load_dwordx4 v[148:151], v136, s[40:41] offset:2048
	global_load_dwordx4 v[152:155], v136, s[40:41] offset:3072
	global_load_dwordx4 v[156:159], v137, s[40:41]
	global_load_dwordx4 v[160:163], v137, s[40:41] offset:1024
	global_load_dwordx4 v[164:167], v137, s[40:41] offset:2048
	global_load_dwordx4 v[168:171], v137, s[40:41] offset:3072
	s_waitcnt vmcnt(8)
	v_pk_mul_f32 v[128:129], v[96:97], v[96:97]
	v_pk_fma_f32 v[128:129], v[98:99], v[98:99], v[128:129]
	v_pk_fma_f32 v[128:129], v[100:101], v[100:101], v[128:129]
	v_pk_fma_f32 v[128:129], v[102:103], v[102:103], v[128:129]
	v_pk_fma_f32 v[128:129], v[104:105], v[104:105], v[128:129]
	v_pk_fma_f32 v[128:129], v[106:107], v[106:107], v[128:129]
	v_pk_fma_f32 v[128:129], v[108:109], v[108:109], v[128:129]
	v_pk_fma_f32 v[128:129], v[110:111], v[110:111], v[128:129]
	v_pk_fma_f32 v[128:129], v[112:113], v[112:113], v[128:129]
	v_pk_fma_f32 v[128:129], v[114:115], v[114:115], v[128:129]
	v_pk_fma_f32 v[128:129], v[116:117], v[116:117], v[128:129]
	v_pk_fma_f32 v[128:129], v[118:119], v[118:119], v[128:129]
	v_pk_fma_f32 v[128:129], v[120:121], v[120:121], v[128:129]
	v_pk_fma_f32 v[128:129], v[122:123], v[122:123], v[128:129]
	v_pk_fma_f32 v[128:129], v[124:125], v[124:125], v[128:129]
	v_pk_fma_f32 v[128:129], v[126:127], v[126:127], v[128:129]
	v_add_f32_e32 v130, v128, v129
	s_nop 1
	v_add_f32_dpp v130, v130, v130 quad_perm:[1,0,3,2] row_mask:0xf bank_mask:0xf bound_ctrl:1
	s_nop 1
	v_add_f32_dpp v130, v130, v130 quad_perm:[2,3,0,1] row_mask:0xf bank_mask:0xf bound_ctrl:1
	s_nop 1
	v_add_f32_dpp v130, v130, v130 row_half_mirror row_mask:0xf bank_mask:0xf bound_ctrl:1
	s_nop 1
	v_add_f32_dpp v130, v130, v130 row_mirror row_mask:0xf bank_mask:0xf bound_ctrl:1
	s_nop 0
	v_readlane_b32 s14, v130, 0
	v_readlane_b32 s15, v130, 16
	v_readlane_b32 s6, v130, 32
	v_readlane_b32 s19, v130, 48
	s_nop 0
	v_mov_b32_e32 v128, s15
	v_add_f32_e32 v128, s14, v128
	v_mov_b32_e32 v129, s19
	v_add_f32_e32 v129, s6, v129
	v_add_f32_e32 v128, v128, v129
	v_mov_b32_e32 v129, 0x358637bd
	v_fmamk_f32 v128, v128, 0x3a000000, v129
	v_rsq_f32_e32 v128, v128
	s_nop 0
	v_readfirstlane_b32 s54, v128
	s_nop 1
	v_pk_mul_f32 v[96:97], v[96:97], s[54:55] op_sel_hi:[1,0]
	v_pk_mul_f32 v[98:99], v[98:99], s[54:55] op_sel_hi:[1,0]
	v_pk_mul_f32 v[96:97], v[96:97], v[0:1]
	v_pk_mul_f32 v[98:99], v[98:99], v[2:3]
	v_pk_mul_f32 v[100:101], v[100:101], s[54:55] op_sel_hi:[1,0]
	v_pk_mul_f32 v[102:103], v[102:103], s[54:55] op_sel_hi:[1,0]
	v_pk_mul_f32 v[100:101], v[100:101], v[4:5]
	v_pk_mul_f32 v[102:103], v[102:103], v[6:7]
	v_pk_mul_f32 v[104:105], v[104:105], s[54:55] op_sel_hi:[1,0]
	v_pk_mul_f32 v[106:107], v[106:107], s[54:55] op_sel_hi:[1,0]
	v_pk_mul_f32 v[104:105], v[104:105], v[8:9]
	v_pk_mul_f32 v[106:107], v[106:107], v[10:11]
	v_pk_mul_f32 v[108:109], v[108:109], s[54:55] op_sel_hi:[1,0]
	v_pk_mul_f32 v[110:111], v[110:111], s[54:55] op_sel_hi:[1,0]
	v_pk_mul_f32 v[108:109], v[108:109], v[12:13]
	v_pk_mul_f32 v[110:111], v[110:111], v[14:15]
	v_pk_mul_f32 v[112:113], v[112:113], s[54:55] op_sel_hi:[1,0]
	v_pk_mul_f32 v[114:115], v[114:115], s[54:55] op_sel_hi:[1,0]
	v_pk_mul_f32 v[112:113], v[112:113], v[16:17]
	v_pk_mul_f32 v[114:115], v[114:115], v[18:19]
	v_pk_mul_f32 v[116:117], v[116:117], s[54:55] op_sel_hi:[1,0]
	v_pk_mul_f32 v[118:119], v[118:119], s[54:55] op_sel_hi:[1,0]
	v_pk_mul_f32 v[116:117], v[116:117], v[20:21]
	v_pk_mul_f32 v[118:119], v[118:119], v[22:23]
	v_pk_mul_f32 v[120:121], v[120:121], s[54:55] op_sel_hi:[1,0]
	v_pk_mul_f32 v[122:123], v[122:123], s[54:55] op_sel_hi:[1,0]
	v_pk_mul_f32 v[120:121], v[120:121], v[24:25]
	v_pk_mul_f32 v[122:123], v[122:123], v[26:27]
	v_pk_mul_f32 v[124:125], v[124:125], s[54:55] op_sel_hi:[1,0]
	v_pk_mul_f32 v[126:127], v[126:127], s[54:55] op_sel_hi:[1,0]
	v_pk_mul_f32 v[124:125], v[124:125], v[28:29]
	v_pk_mul_f32 v[126:127], v[126:127], v[30:31]
	global_store_dwordx4 v132, v[96:99], s[40:41]
	global_store_dwordx4 v132, v[100:103], s[40:41] offset:1024
	global_store_dwordx4 v132, v[104:107], s[40:41] offset:2048
	global_store_dwordx4 v132, v[108:111], s[40:41] offset:3072
	global_store_dwordx4 v134, v[112:115], s[40:41]
	global_store_dwordx4 v134, v[116:119], s[40:41] offset:1024
	global_store_dwordx4 v134, v[120:123], s[40:41] offset:2048
	global_store_dwordx4 v134, v[124:127], s[40:41] offset:3072
	v_add_u32_e32 v132, 0x1000000, v132
	v_add_u32_e32 v134, 0x1000000, v134
	v_add_u32_e32 v136, 0x1000000, v136
	v_add_u32_e32 v137, 0x1000000, v137
	global_load_dwordx4 v[96:99], v136, s[40:41]
	global_load_dwordx4 v[100:103], v136, s[40:41] offset:1024
	global_load_dwordx4 v[104:107], v136, s[40:41] offset:2048
	global_load_dwordx4 v[108:111], v136, s[40:41] offset:3072
	global_load_dwordx4 v[112:115], v137, s[40:41]
	global_load_dwordx4 v[116:119], v137, s[40:41] offset:1024
	global_load_dwordx4 v[120:123], v137, s[40:41] offset:2048
	global_load_dwordx4 v[124:127], v137, s[40:41] offset:3072
	s_waitcnt vmcnt(16)
; #define FIN_LOAD(V, R_) { const float* s = p->out + (size_t)(R_) * DM; UFOR(j, 8) V[j] = *(const float4*)(s + j * 256 + lane * 4); }
; __device__ __forceinline__ void phase_final(KP p) {
;     ...
;   int r = bid_ * 8 + wv;
;   if (r < ML) FIN_LOAD(va, r);
;   for (; r < ML; r += 2 * stride) {
;     if (r + stride < ML) FIN_LOAD(vb, r + stride);
;     FIN_BODY(va, r);
;     if (r + 2 * stride < ML) FIN_LOAD(va, r + 2 * stride);
;     if (r + stride < ML) FIN_BODY(vb, r + stride);
;   }
	v_pk_mul_f32 v[128:129], v[140:141], v[140:141]
	v_pk_fma_f32 v[128:129], v[142:143], v[142:143], v[128:129]
	v_pk_fma_f32 v[128:129], v[144:145], v[144:145], v[128:129]
	v_pk_fma_f32 v[128:129], v[146:147], v[146:147], v[128:129]
	v_pk_fma_f32 v[128:129], v[148:149], v[148:149], v[128:129]
	v_pk_fma_f32 v[128:129], v[150:151], v[150:151], v[128:129]
	v_pk_fma_f32 v[128:129], v[152:153], v[152:153], v[128:129]
	v_pk_fma_f32 v[128:129], v[154:155], v[154:155], v[128:129]
	v_pk_fma_f32 v[128:129], v[156:157], v[156:157], v[128:129]
	v_pk_fma_f32 v[128:129], v[158:159], v[158:159], v[128:129]
	v_pk_fma_f32 v[128:129], v[160:161], v[160:161], v[128:129]
	v_pk_fma_f32 v[128:129], v[162:163], v[162:163], v[128:129]
	v_pk_fma_f32 v[128:129], v[164:165], v[164:165], v[128:129]
	v_pk_fma_f32 v[128:129], v[166:167], v[166:167], v[128:129]
	v_pk_fma_f32 v[128:129], v[168:169], v[168:169], v[128:129]
	v_pk_fma_f32 v[128:129], v[170:171], v[170:171], v[128:129]
	v_add_f32_e32 v130, v128, v129
	s_nop 1
	v_add_f32_dpp v130, v130, v130 quad_perm:[1,0,3,2] row_mask:0xf bank_mask:0xf bound_ctrl:1
	s_nop 1
	v_add_f32_dpp v130, v130, v130 quad_perm:[2,3,0,1] row_mask:0xf bank_mask:0xf bound_ctrl:1
	s_nop 1
	v_add_f32_dpp v130, v130, v130 row_half_mirror row_mask:0xf bank_mask:0xf bound_ctrl:1
	s_nop 1
	v_add_f32_dpp v130, v130, v130 row_mirror row_mask:0xf bank_mask:0xf bound_ctrl:1
	s_nop 0
	v_readlane_b32 s14, v130, 0
	v_readlane_b32 s15, v130, 16
	v_readlane_b32 s6, v130, 32
	v_readlane_b32 s19, v130, 48
	s_nop 0
	v_mov_b32_e32 v128, s15
	v_add_f32_e32 v128, s14, v128
	v_mov_b32_e32 v129, s19
	v_add_f32_e32 v129, s6, v129
	v_add_f32_e32 v128, v128, v129
	v_mov_b32_e32 v129, 0x358637bd
	v_fmamk_f32 v128, v128, 0x3a000000, v129
	v_rsq_f32_e32 v128, v128
	s_nop 0
	v_readfirstlane_b32 s54, v128
	s_nop 1
	v_pk_mul_f32 v[140:141], v[140:141], s[54:55] op_sel_hi:[1,0]
	v_pk_mul_f32 v[142:143], v[142:143], s[54:55] op_sel_hi:[1,0]
	v_pk_mul_f32 v[140:141], v[140:141], v[0:1]
	v_pk_mul_f32 v[142:143], v[142:143], v[2:3]
	v_pk_mul_f32 v[144:145], v[144:145], s[54:55] op_sel_hi:[1,0]
	v_pk_mul_f32 v[146:147], v[146:147], s[54:55] op_sel_hi:[1,0]
	v_pk_mul_f32 v[144:145], v[144:145], v[4:5]
	v_pk_mul_f32 v[146:147], v[146:147], v[6:7]
	v_pk_mul_f32 v[148:149], v[148:149], s[54:55] op_sel_hi:[1,0]
	v_pk_mul_f32 v[150:151], v[150:151], s[54:55] op_sel_hi:[1,0]
	v_pk_mul_f32 v[148:149], v[148:149], v[8:9]
	v_pk_mul_f32 v[150:151], v[150:151], v[10:11]
	v_pk_mul_f32 v[152:153], v[152:153], s[54:55] op_sel_hi:[1,0]
	v_pk_mul_f32 v[154:155], v[154:155], s[54:55] op_sel_hi:[1,0]
	v_pk_mul_f32 v[152:153], v[152:153], v[12:13]
	v_pk_mul_f32 v[154:155], v[154:155], v[14:15]
	v_pk_mul_f32 v[156:157], v[156:157], s[54:55] op_sel_hi:[1,0]
	v_pk_mul_f32 v[158:159], v[158:159], s[54:55] op_sel_hi:[1,0]
	v_pk_mul_f32 v[156:157], v[156:157], v[16:17]
	v_pk_mul_f32 v[158:159], v[158:159], v[18:19]
	v_pk_mul_f32 v[160:161], v[160:161], s[54:55] op_sel_hi:[1,0]
	v_pk_mul_f32 v[162:163], v[162:163], s[54:55] op_sel_hi:[1,0]
	v_pk_mul_f32 v[160:161], v[160:161], v[20:21]
	v_pk_mul_f32 v[162:163], v[162:163], v[22:23]
	v_pk_mul_f32 v[164:165], v[164:165], s[54:55] op_sel_hi:[1,0]
	v_pk_mul_f32 v[166:167], v[166:167], s[54:55] op_sel_hi:[1,0]
	v_pk_mul_f32 v[164:165], v[164:165], v[24:25]
	v_pk_mul_f32 v[166:167], v[166:167], v[26:27]
	v_pk_mul_f32 v[168:169], v[168:169], s[54:55] op_sel_hi:[1,0]
	v_pk_mul_f32 v[170:171], v[170:171], s[54:55] op_sel_hi:[1,0]
	v_pk_mul_f32 v[168:169], v[168:169], v[28:29]
	v_pk_mul_f32 v[170:171], v[170:171], v[30:31]
	global_store_dwordx4 v132, v[140:143], s[40:41]
	global_store_dwordx4 v132, v[144:147], s[40:41] offset:1024
	global_store_dwordx4 v132, v[148:151], s[40:41] offset:2048
	global_store_dwordx4 v132, v[152:155], s[40:41] offset:3072
	global_store_dwordx4 v134, v[156:159], s[40:41]
	global_store_dwordx4 v134, v[160:163], s[40:41] offset:1024
	global_store_dwordx4 v134, v[164:167], s[40:41] offset:2048
	global_store_dwordx4 v134, v[168:171], s[40:41] offset:3072
	v_add_u32_e32 v132, 0x1000000, v132
	v_add_u32_e32 v134, 0x1000000, v134
	v_add_u32_e32 v136, 0x1000000, v136
	v_add_u32_e32 v137, 0x1000000, v137
	global_load_dwordx4 v[140:143], v136, s[40:41]
	global_load_dwordx4 v[144:147], v136, s[40:41] offset:1024
	global_load_dwordx4 v[148:151], v136, s[40:41] offset:2048
	global_load_dwordx4 v[152:155], v136, s[40:41] offset:3072
	global_load_dwordx4 v[156:159], v137, s[40:41]
	global_load_dwordx4 v[160:163], v137, s[40:41] offset:1024
	global_load_dwordx4 v[164:167], v137, s[40:41] offset:2048
	global_load_dwordx4 v[168:171], v137, s[40:41] offset:3072
	s_waitcnt vmcnt(16)
; #define FIN_LOAD(V, R_) { const float* s = p->out + (size_t)(R_) * DM; UFOR(j, 8) V[j] = *(const float4*)(s + j * 256 + lane * 4); }
; __device__ __forceinline__ void phase_final(KP p) {
;     ...
;   int r = bid_ * 8 + wv;
;   if (r < ML) FIN_LOAD(va, r);
;   for (; r < ML; r += 2 * stride) {
;     if (r + stride < ML) FIN_LOAD(vb, r + stride);
;     FIN_BODY(va, r);
;     if (r + 2 * stride < ML) FIN_LOAD(va, r + 2 * stride);
;     if (r + stride < ML) FIN_BODY(vb, r + stride);
;   }
	v_pk_mul_f32 v[128:129], v[96:97], v[96:97]
	v_pk_fma_f32 v[128:129], v[98:99], v[98:99], v[128:129]
	v_pk_fma_f32 v[128:129], v[100:101], v[100:101], v[128:129]
	v_pk_fma_f32 v[128:129], v[102:103], v[102:103], v[128:129]
	v_pk_fma_f32 v[128:129], v[104:105], v[104:105], v[128:129]
	v_pk_fma_f32 v[128:129], v[106:107], v[106:107], v[128:129]
	v_pk_fma_f32 v[128:129], v[108:109], v[108:109], v[128:129]
	v_pk_fma_f32 v[128:129], v[110:111], v[110:111], v[128:129]
	v_pk_fma_f32 v[128:129], v[112:113], v[112:113], v[128:129]
	v_pk_fma_f32 v[128:129], v[114:115], v[114:115], v[128:129]
	v_pk_fma_f32 v[128:129], v[116:117], v[116:117], v[128:129]
	v_pk_fma_f32 v[128:129], v[118:119], v[118:119], v[128:129]
	v_pk_fma_f32 v[128:129], v[120:121], v[120:121], v[128:129]
	v_pk_fma_f32 v[128:129], v[122:123], v[122:123], v[128:129]
	v_pk_fma_f32 v[128:129], v[124:125], v[124:125], v[128:129]
	v_pk_fma_f32 v[128:129], v[126:127], v[126:127], v[128:129]
	v_add_f32_e32 v130, v128, v129
	s_nop 1
	v_add_f32_dpp v130, v130, v130 quad_perm:[1,0,3,2] row_mask:0xf bank_mask:0xf bound_ctrl:1
	s_nop 1
	v_add_f32_dpp v130, v130, v130 quad_perm:[2,3,0,1] row_mask:0xf bank_mask:0xf bound_ctrl:1
	s_nop 1
	v_add_f32_dpp v130, v130, v130 row_half_mirror row_mask:0xf bank_mask:0xf bound_ctrl:1
	s_nop 1
	v_add_f32_dpp v130, v130, v130 row_mirror row_mask:0xf bank_mask:0xf bound_ctrl:1
	s_nop 0
	v_readlane_b32 s14, v130, 0
	v_readlane_b32 s15, v130, 16
	v_readlane_b32 s6, v130, 32
	v_readlane_b32 s19, v130, 48
	s_nop 0
	v_mov_b32_e32 v128, s15
	v_add_f32_e32 v128, s14, v128
	v_mov_b32_e32 v129, s19
	v_add_f32_e32 v129, s6, v129
	v_add_f32_e32 v128, v128, v129
	v_mov_b32_e32 v129, 0x358637bd
	v_fmamk_f32 v128, v128, 0x3a000000, v129
	v_rsq_f32_e32 v128, v128
	s_nop 0
	v_readfirstlane_b32 s54, v128
	s_nop 1
	v_pk_mul_f32 v[96:97], v[96:97], s[54:55] op_sel_hi:[1,0]
	v_pk_mul_f32 v[98:99], v[98:99], s[54:55] op_sel_hi:[1,0]
	v_pk_mul_f32 v[96:97], v[96:97], v[0:1]
	v_pk_mul_f32 v[98:99], v[98:99], v[2:3]
	v_pk_mul_f32 v[100:101], v[100:101], s[54:55] op_sel_hi:[1,0]
	v_pk_mul_f32 v[102:103], v[102:103], s[54:55] op_sel_hi:[1,0]
	v_pk_mul_f32 v[100:101], v[100:101], v[4:5]
	v_pk_mul_f32 v[102:103], v[102:103], v[6:7]
	v_pk_mul_f32 v[104:105], v[104:105], s[54:55] op_sel_hi:[1,0]
	v_pk_mul_f32 v[106:107], v[106:107], s[54:55] op_sel_hi:[1,0]
	v_pk_mul_f32 v[104:105], v[104:105], v[8:9]
	v_pk_mul_f32 v[106:107], v[106:107], v[10:11]
	v_pk_mul_f32 v[108:109], v[108:109], s[54:55] op_sel_hi:[1,0]
	v_pk_mul_f32 v[110:111], v[110:111], s[54:55] op_sel_hi:[1,0]
	v_pk_mul_f32 v[108:109], v[108:109], v[12:13]
	v_pk_mul_f32 v[110:111], v[110:111], v[14:15]
	v_pk_mul_f32 v[112:113], v[112:113], s[54:55] op_sel_hi:[1,0]
	v_pk_mul_f32 v[114:115], v[114:115], s[54:55] op_sel_hi:[1,0]
	v_pk_mul_f32 v[112:113], v[112:113], v[16:17]
	v_pk_mul_f32 v[114:115], v[114:115], v[18:19]
	v_pk_mul_f32 v[116:117], v[116:117], s[54:55] op_sel_hi:[1,0]
	v_pk_mul_f32 v[118:119], v[118:119], s[54:55] op_sel_hi:[1,0]
	v_pk_mul_f32 v[116:117], v[116:117], v[20:21]
	v_pk_mul_f32 v[118:119], v[118:119], v[22:23]
	v_pk_mul_f32 v[120:121], v[120:121], s[54:55] op_sel_hi:[1,0]
	v_pk_mul_f32 v[122:123], v[122:123], s[54:55] op_sel_hi:[1,0]
	v_pk_mul_f32 v[120:121], v[120:121], v[24:25]
	v_pk_mul_f32 v[122:123], v[122:123], v[26:27]
	v_pk_mul_f32 v[124:125], v[124:125], s[54:55] op_sel_hi:[1,0]
	v_pk_mul_f32 v[126:127], v[126:127], s[54:55] op_sel_hi:[1,0]
	v_pk_mul_f32 v[124:125], v[124:125], v[28:29]
	v_pk_mul_f32 v[126:127], v[126:127], v[30:31]
	global_store_dwordx4 v132, v[96:99], s[40:41]
	global_store_dwordx4 v132, v[100:103], s[40:41] offset:1024
	global_store_dwordx4 v132, v[104:107], s[40:41] offset:2048
	global_store_dwordx4 v132, v[108:111], s[40:41] offset:3072
	global_store_dwordx4 v134, v[112:115], s[40:41]
	global_store_dwordx4 v134, v[116:119], s[40:41] offset:1024
	global_store_dwordx4 v134, v[120:123], s[40:41] offset:2048
	global_store_dwordx4 v134, v[124:127], s[40:41] offset:3072
	v_add_u32_e32 v132, 0x1000000, v132
	v_add_u32_e32 v134, 0x1000000, v134
	v_add_u32_e32 v136, 0x1000000, v136
	v_add_u32_e32 v137, 0x1000000, v137
	global_load_dwordx4 v[96:99], v136, s[40:41]
	global_load_dwordx4 v[100:103], v136, s[40:41] offset:1024
	global_load_dwordx4 v[104:107], v136, s[40:41] offset:2048
	global_load_dwordx4 v[108:111], v136, s[40:41] offset:3072
	global_load_dwordx4 v[112:115], v137, s[40:41]
	global_load_dwordx4 v[116:119], v137, s[40:41] offset:1024
	global_load_dwordx4 v[120:123], v137, s[40:41] offset:2048
	global_load_dwordx4 v[124:127], v137, s[40:41] offset:3072
	s_waitcnt vmcnt(16)
; #define FIN_LOAD(V, R_) { const float* s = p->out + (size_t)(R_) * DM; UFOR(j, 8) V[j] = *(const float4*)(s + j * 256 + lane * 4); }
; __device__ __forceinline__ void phase_final(KP p) {
;     ...
;   int r = bid_ * 8 + wv;
;   if (r < ML) FIN_LOAD(va, r);
;   for (; r < ML; r += 2 * stride) {
;     if (r + stride < ML) FIN_LOAD(vb, r + stride);
;     FIN_BODY(va, r);
;     if (r + 2 * stride < ML) FIN_LOAD(va, r + 2 * stride);
;     if (r + stride < ML) FIN_BODY(vb, r + stride);
;   }
	v_pk_mul_f32 v[128:129], v[140:141], v[140:141]
	v_pk_fma_f32 v[128:129], v[142:143], v[142:143], v[128:129]
	v_pk_fma_f32 v[128:129], v[144:145], v[144:145], v[128:129]
	v_pk_fma_f32 v[128:129], v[146:147], v[146:147], v[128:129]
	v_pk_fma_f32 v[128:129], v[148:149], v[148:149], v[128:129]
	v_pk_fma_f32 v[128:129], v[150:151], v[150:151], v[128:129]
	v_pk_fma_f32 v[128:129], v[152:153], v[152:153], v[128:129]
	v_pk_fma_f32 v[128:129], v[154:155], v[154:155], v[128:129]
	v_pk_fma_f32 v[128:129], v[156:157], v[156:157], v[128:129]
	v_pk_fma_f32 v[128:129], v[158:159], v[158:159], v[128:129]
	v_pk_fma_f32 v[128:129], v[160:161], v[160:161], v[128:129]
	v_pk_fma_f32 v[128:129], v[162:163], v[162:163], v[128:129]
	v_pk_fma_f32 v[128:129], v[164:165], v[164:165], v[128:129]
	v_pk_fma_f32 v[128:129], v[166:167], v[166:167], v[128:129]
	v_pk_fma_f32 v[128:129], v[168:169], v[168:169], v[128:129]
	v_pk_fma_f32 v[128:129], v[170:171], v[170:171], v[128:129]
	v_add_f32_e32 v130, v128, v129
	s_nop 1
	v_add_f32_dpp v130, v130, v130 quad_perm:[1,0,3,2] row_mask:0xf bank_mask:0xf bound_ctrl:1
	s_nop 1
	v_add_f32_dpp v130, v130, v130 quad_perm:[2,3,0,1] row_mask:0xf bank_mask:0xf bound_ctrl:1
	s_nop 1
	v_add_f32_dpp v130, v130, v130 row_half_mirror row_mask:0xf bank_mask:0xf bound_ctrl:1
	s_nop 1
	v_add_f32_dpp v130, v130, v130 row_mirror row_mask:0xf bank_mask:0xf bound_ctrl:1
	s_nop 0
	v_readlane_b32 s14, v130, 0
	v_readlane_b32 s15, v130, 16
	v_readlane_b32 s6, v130, 32
	v_readlane_b32 s19, v130, 48
	s_nop 0
	v_mov_b32_e32 v128, s15
	v_add_f32_e32 v128, s14, v128
	v_mov_b32_e32 v129, s19
	v_add_f32_e32 v129, s6, v129
	v_add_f32_e32 v128, v128, v129
	v_mov_b32_e32 v129, 0x358637bd
	v_fmamk_f32 v128, v128, 0x3a000000, v129
	v_rsq_f32_e32 v128, v128
	s_nop 0
	v_readfirstlane_b32 s54, v128
	s_nop 1
	v_pk_mul_f32 v[140:141], v[140:141], s[54:55] op_sel_hi:[1,0]
	v_pk_mul_f32 v[142:143], v[142:143], s[54:55] op_sel_hi:[1,0]
	v_pk_mul_f32 v[140:141], v[140:141], v[0:1]
	v_pk_mul_f32 v[142:143], v[142:143], v[2:3]
	v_pk_mul_f32 v[144:145], v[144:145], s[54:55] op_sel_hi:[1,0]
	v_pk_mul_f32 v[146:147], v[146:147], s[54:55] op_sel_hi:[1,0]
	v_pk_mul_f32 v[144:145], v[144:145], v[4:5]
	v_pk_mul_f32 v[146:147], v[146:147], v[6:7]
	v_pk_mul_f32 v[148:149], v[148:149], s[54:55] op_sel_hi:[1,0]
	v_pk_mul_f32 v[150:151], v[150:151], s[54:55] op_sel_hi:[1,0]
	v_pk_mul_f32 v[148:149], v[148:149], v[8:9]
	v_pk_mul_f32 v[150:151], v[150:151], v[10:11]
	v_pk_mul_f32 v[152:153], v[152:153], s[54:55] op_sel_hi:[1,0]
	v_pk_mul_f32 v[154:155], v[154:155], s[54:55] op_sel_hi:[1,0]
	v_pk_mul_f32 v[152:153], v[152:153], v[12:13]
	v_pk_mul_f32 v[154:155], v[154:155], v[14:15]
	v_pk_mul_f32 v[156:157], v[156:157], s[54:55] op_sel_hi:[1,0]
	v_pk_mul_f32 v[158:159], v[158:159], s[54:55] op_sel_hi:[1,0]
	v_pk_mul_f32 v[156:157], v[156:157], v[16:17]
	v_pk_mul_f32 v[158:159], v[158:159], v[18:19]
	v_pk_mul_f32 v[160:161], v[160:161], s[54:55] op_sel_hi:[1,0]
	v_pk_mul_f32 v[162:163], v[162:163], s[54:55] op_sel_hi:[1,0]
	v_pk_mul_f32 v[160:161], v[160:161], v[20:21]
	v_pk_mul_f32 v[162:163], v[162:163], v[22:23]
	v_pk_mul_f32 v[164:165], v[164:165], s[54:55] op_sel_hi:[1,0]
	v_pk_mul_f32 v[166:167], v[166:167], s[54:55] op_sel_hi:[1,0]
	v_pk_mul_f32 v[164:165], v[164:165], v[24:25]
	v_pk_mul_f32 v[166:167], v[166:167], v[26:27]
	v_pk_mul_f32 v[168:169], v[168:169], s[54:55] op_sel_hi:[1,0]
	v_pk_mul_f32 v[170:171], v[170:171], s[54:55] op_sel_hi:[1,0]
	v_pk_mul_f32 v[168:169], v[168:169], v[28:29]
	v_pk_mul_f32 v[170:171], v[170:171], v[30:31]
	global_store_dwordx4 v132, v[140:143], s[40:41]
	global_store_dwordx4 v132, v[144:147], s[40:41] offset:1024
	global_store_dwordx4 v132, v[148:151], s[40:41] offset:2048
	global_store_dwordx4 v132, v[152:155], s[40:41] offset:3072
	global_store_dwordx4 v134, v[156:159], s[40:41]
	global_store_dwordx4 v134, v[160:163], s[40:41] offset:1024
	global_store_dwordx4 v134, v[164:167], s[40:41] offset:2048
	global_store_dwordx4 v134, v[168:171], s[40:41] offset:3072
	v_add_u32_e32 v132, 0x1000000, v132
	v_add_u32_e32 v134, 0x1000000, v134
	v_add_u32_e32 v136, 0x1000000, v136
	v_add_u32_e32 v137, 0x1000000, v137
	global_load_dwordx4 v[140:143], v136, s[40:41]
	global_load_dwordx4 v[144:147], v136, s[40:41] offset:1024
	global_load_dwordx4 v[148:151], v136, s[40:41] offset:2048
	global_load_dwordx4 v[152:155], v136, s[40:41] offset:3072
	global_load_dwordx4 v[156:159], v137, s[40:41]
	global_load_dwordx4 v[160:163], v137, s[40:41] offset:1024
	global_load_dwordx4 v[164:167], v137, s[40:41] offset:2048
	global_load_dwordx4 v[168:171], v137, s[40:41] offset:3072
	s_waitcnt vmcnt(16)
; #define FIN_LOAD(V, R_) { const float* s = p->out + (size_t)(R_) * DM; UFOR(j, 8) V[j] = *(const float4*)(s + j * 256 + lane * 4); }
; __device__ __forceinline__ void phase_final(KP p) {
;     ...
;   int r = bid_ * 8 + wv;
;   if (r < ML) FIN_LOAD(va, r);
;   for (; r < ML; r += 2 * stride) {
;     if (r + stride < ML) FIN_LOAD(vb, r + stride);
;     FIN_BODY(va, r);
;     if (r + 2 * stride < ML) FIN_LOAD(va, r + 2 * stride);
;     if (r + stride < ML) FIN_BODY(vb, r + stride);
;   }
	v_pk_mul_f32 v[128:129], v[96:97], v[96:97]
	v_pk_fma_f32 v[128:129], v[98:99], v[98:99], v[128:129]
	v_pk_fma_f32 v[128:129], v[100:101], v[100:101], v[128:129]
	v_pk_fma_f32 v[128:129], v[102:103], v[102:103], v[128:129]
	v_pk_fma_f32 v[128:129], v[104:105], v[104:105], v[128:129]
	v_pk_fma_f32 v[128:129], v[106:107], v[106:107], v[128:129]
	v_pk_fma_f32 v[128:129], v[108:109], v[108:109], v[128:129]
	v_pk_fma_f32 v[128:129], v[110:111], v[110:111], v[128:129]
	v_pk_fma_f32 v[128:129], v[112:113], v[112:113], v[128:129]
	v_pk_fma_f32 v[128:129], v[114:115], v[114:115], v[128:129]
	v_pk_fma_f32 v[128:129], v[116:117], v[116:117], v[128:129]
	v_pk_fma_f32 v[128:129], v[118:119], v[118:119], v[128:129]
	v_pk_fma_f32 v[128:129], v[120:121], v[120:121], v[128:129]
	v_pk_fma_f32 v[128:129], v[122:123], v[122:123], v[128:129]
	v_pk_fma_f32 v[128:129], v[124:125], v[124:125], v[128:129]
	v_pk_fma_f32 v[128:129], v[126:127], v[126:127], v[128:129]
	v_add_f32_e32 v130, v128, v129
	s_nop 1
	v_add_f32_dpp v130, v130, v130 quad_perm:[1,0,3,2] row_mask:0xf bank_mask:0xf bound_ctrl:1
	s_nop 1
	v_add_f32_dpp v130, v130, v130 quad_perm:[2,3,0,1] row_mask:0xf bank_mask:0xf bound_ctrl:1
	s_nop 1
	v_add_f32_dpp v130, v130, v130 row_half_mirror row_mask:0xf bank_mask:0xf bound_ctrl:1
	s_nop 1
	v_add_f32_dpp v130, v130, v130 row_mirror row_mask:0xf bank_mask:0xf bound_ctrl:1
	s_nop 0
	v_readlane_b32 s14, v130, 0
	v_readlane_b32 s15, v130, 16
	v_readlane_b32 s6, v130, 32
	v_readlane_b32 s19, v130, 48
	s_nop 0
	v_mov_b32_e32 v128, s15
	v_add_f32_e32 v128, s14, v128
	v_mov_b32_e32 v129, s19
	v_add_f32_e32 v129, s6, v129
	v_add_f32_e32 v128, v128, v129
	v_mov_b32_e32 v129, 0x358637bd
	v_fmamk_f32 v128, v128, 0x3a000000, v129
	v_rsq_f32_e32 v128, v128
	s_nop 0
	v_readfirstlane_b32 s54, v128
	s_nop 1
	v_pk_mul_f32 v[96:97], v[96:97], s[54:55] op_sel_hi:[1,0]
	v_pk_mul_f32 v[98:99], v[98:99], s[54:55] op_sel_hi:[1,0]
	v_pk_mul_f32 v[96:97], v[96:97], v[0:1]
	v_pk_mul_f32 v[98:99], v[98:99], v[2:3]
	v_pk_mul_f32 v[100:101], v[100:101], s[54:55] op_sel_hi:[1,0]
	v_pk_mul_f32 v[102:103], v[102:103], s[54:55] op_sel_hi:[1,0]
	v_pk_mul_f32 v[100:101], v[100:101], v[4:5]
	v_pk_mul_f32 v[102:103], v[102:103], v[6:7]
	v_pk_mul_f32 v[104:105], v[104:105], s[54:55] op_sel_hi:[1,0]
	v_pk_mul_f32 v[106:107], v[106:107], s[54:55] op_sel_hi:[1,0]
	v_pk_mul_f32 v[104:105], v[104:105], v[8:9]
	v_pk_mul_f32 v[106:107], v[106:107], v[10:11]
	v_pk_mul_f32 v[108:109], v[108:109], s[54:55] op_sel_hi:[1,0]
	v_pk_mul_f32 v[110:111], v[110:111], s[54:55] op_sel_hi:[1,0]
	v_pk_mul_f32 v[108:109], v[108:109], v[12:13]
	v_pk_mul_f32 v[110:111], v[110:111], v[14:15]
	v_pk_mul_f32 v[112:113], v[112:113], s[54:55] op_sel_hi:[1,0]
	v_pk_mul_f32 v[114:115], v[114:115], s[54:55] op_sel_hi:[1,0]
	v_pk_mul_f32 v[112:113], v[112:113], v[16:17]
	v_pk_mul_f32 v[114:115], v[114:115], v[18:19]
	v_pk_mul_f32 v[116:117], v[116:117], s[54:55] op_sel_hi:[1,0]
	v_pk_mul_f32 v[118:119], v[118:119], s[54:55] op_sel_hi:[1,0]
	v_pk_mul_f32 v[116:117], v[116:117], v[20:21]
	v_pk_mul_f32 v[118:119], v[118:119], v[22:23]
	v_pk_mul_f32 v[120:121], v[120:121], s[54:55] op_sel_hi:[1,0]
	v_pk_mul_f32 v[122:123], v[122:123], s[54:55] op_sel_hi:[1,0]
	v_pk_mul_f32 v[120:121], v[120:121], v[24:25]
	v_pk_mul_f32 v[122:123], v[122:123], v[26:27]
	v_pk_mul_f32 v[124:125], v[124:125], s[54:55] op_sel_hi:[1,0]
	v_pk_mul_f32 v[126:127], v[126:127], s[54:55] op_sel_hi:[1,0]
	v_pk_mul_f32 v[124:125], v[124:125], v[28:29]
	v_pk_mul_f32 v[126:127], v[126:127], v[30:31]
	global_store_dwordx4 v132, v[96:99], s[40:41]
	global_store_dwordx4 v132, v[100:103], s[40:41] offset:1024
	global_store_dwordx4 v132, v[104:107], s[40:41] offset:2048
	global_store_dwordx4 v132, v[108:111], s[40:41] offset:3072
	global_store_dwordx4 v134, v[112:115], s[40:41]
	global_store_dwordx4 v134, v[116:119], s[40:41] offset:1024
	global_store_dwordx4 v134, v[120:123], s[40:41] offset:2048
	global_store_dwordx4 v134, v[124:127], s[40:41] offset:3072
	v_add_u32_e32 v132, 0x1000000, v132
	v_add_u32_e32 v134, 0x1000000, v134
	v_add_u32_e32 v136, 0x1000000, v136
	v_add_u32_e32 v137, 0x1000000, v137
	global_load_dwordx4 v[96:99], v136, s[40:41]
	global_load_dwordx4 v[100:103], v136, s[40:41] offset:1024
	global_load_dwordx4 v[104:107], v136, s[40:41] offset:2048
	global_load_dwordx4 v[108:111], v136, s[40:41] offset:3072
	global_load_dwordx4 v[112:115], v137, s[40:41]
	global_load_dwordx4 v[116:119], v137, s[40:41] offset:1024
	global_load_dwordx4 v[120:123], v137, s[40:41] offset:2048
	global_load_dwordx4 v[124:127], v137, s[40:41] offset:3072
	s_waitcnt vmcnt(16)
; #define FIN_LOAD(V, R_) { const float* s = p->out + (size_t)(R_) * DM; UFOR(j, 8) V[j] = *(const float4*)(s + j * 256 + lane * 4); }
; __device__ __forceinline__ void phase_final(KP p) {
;     ...
;   int r = bid_ * 8 + wv;
;   if (r < ML) FIN_LOAD(va, r);
;   for (; r < ML; r += 2 * stride) {
;     if (r + stride < ML) FIN_LOAD(vb, r + stride);
;     FIN_BODY(va, r);
;     if (r + 2 * stride < ML) FIN_LOAD(va, r + 2 * stride);
;     if (r + stride < ML) FIN_BODY(vb, r + stride);
;   }
	v_pk_mul_f32 v[128:129], v[140:141], v[140:141]
	v_pk_fma_f32 v[128:129], v[142:143], v[142:143], v[128:129]
	v_pk_fma_f32 v[128:129], v[144:145], v[144:145], v[128:129]
	v_pk_fma_f32 v[128:129], v[146:147], v[146:147], v[128:129]
	v_pk_fma_f32 v[128:129], v[148:149], v[148:149], v[128:129]
	v_pk_fma_f32 v[128:129], v[150:151], v[150:151], v[128:129]
	v_pk_fma_f32 v[128:129], v[152:153], v[152:153], v[128:129]
	v_pk_fma_f32 v[128:129], v[154:155], v[154:155], v[128:129]
	v_pk_fma_f32 v[128:129], v[156:157], v[156:157], v[128:129]
	v_pk_fma_f32 v[128:129], v[158:159], v[158:159], v[128:129]
	v_pk_fma_f32 v[128:129], v[160:161], v[160:161], v[128:129]
	v_pk_fma_f32 v[128:129], v[162:163], v[162:163], v[128:129]
	v_pk_fma_f32 v[128:129], v[164:165], v[164:165], v[128:129]
	v_pk_fma_f32 v[128:129], v[166:167], v[166:167], v[128:129]
	v_pk_fma_f32 v[128:129], v[168:169], v[168:169], v[128:129]
	v_pk_fma_f32 v[128:129], v[170:171], v[170:171], v[128:129]
	v_add_f32_e32 v130, v128, v129
	s_nop 1
	v_add_f32_dpp v130, v130, v130 quad_perm:[1,0,3,2] row_mask:0xf bank_mask:0xf bound_ctrl:1
	s_nop 1
	v_add_f32_dpp v130, v130, v130 quad_perm:[2,3,0,1] row_mask:0xf bank_mask:0xf bound_ctrl:1
	s_nop 1
	v_add_f32_dpp v130, v130, v130 row_half_mirror row_mask:0xf bank_mask:0xf bound_ctrl:1
	s_nop 1
	v_add_f32_dpp v130, v130, v130 row_mirror row_mask:0xf bank_mask:0xf bound_ctrl:1
	s_nop 0
	v_readlane_b32 s14, v130, 0
	v_readlane_b32 s15, v130, 16
	v_readlane_b32 s6, v130, 32
	v_readlane_b32 s19, v130, 48
	s_nop 0
	v_mov_b32_e32 v128, s15
	v_add_f32_e32 v128, s14, v128
	v_mov_b32_e32 v129, s19
	v_add_f32_e32 v129, s6, v129
	v_add_f32_e32 v128, v128, v129
	v_mov_b32_e32 v129, 0x358637bd
	v_fmamk_f32 v128, v128, 0x3a000000, v129
	v_rsq_f32_e32 v128, v128
	s_nop 0
	v_readfirstlane_b32 s54, v128
	s_nop 1
	v_pk_mul_f32 v[140:141], v[140:141], s[54:55] op_sel_hi:[1,0]
	v_pk_mul_f32 v[142:143], v[142:143], s[54:55] op_sel_hi:[1,0]
	v_pk_mul_f32 v[140:141], v[140:141], v[0:1]
	v_pk_mul_f32 v[142:143], v[142:143], v[2:3]
	v_pk_mul_f32 v[144:145], v[144:145], s[54:55] op_sel_hi:[1,0]
	v_pk_mul_f32 v[146:147], v[146:147], s[54:55] op_sel_hi:[1,0]
	v_pk_mul_f32 v[144:145], v[144:145], v[4:5]
	v_pk_mul_f32 v[146:147], v[146:147], v[6:7]
	v_pk_mul_f32 v[148:149], v[148:149], s[54:55] op_sel_hi:[1,0]
	v_pk_mul_f32 v[150:151], v[150:151], s[54:55] op_sel_hi:[1,0]
	v_pk_mul_f32 v[148:149], v[148:149], v[8:9]
	v_pk_mul_f32 v[150:151], v[150:151], v[10:11]
	v_pk_mul_f32 v[152:153], v[152:153], s[54:55] op_sel_hi:[1,0]
	v_pk_mul_f32 v[154:155], v[154:155], s[54:55] op_sel_hi:[1,0]
	v_pk_mul_f32 v[152:153], v[152:153], v[12:13]
	v_pk_mul_f32 v[154:155], v[154:155], v[14:15]
	v_pk_mul_f32 v[156:157], v[156:157], s[54:55] op_sel_hi:[1,0]
	v_pk_mul_f32 v[158:159], v[158:159], s[54:55] op_sel_hi:[1,0]
	v_pk_mul_f32 v[156:157], v[156:157], v[16:17]
	v_pk_mul_f32 v[158:159], v[158:159], v[18:19]
	v_pk_mul_f32 v[160:161], v[160:161], s[54:55] op_sel_hi:[1,0]
	v_pk_mul_f32 v[162:163], v[162:163], s[54:55] op_sel_hi:[1,0]
	v_pk_mul_f32 v[160:161], v[160:161], v[20:21]
	v_pk_mul_f32 v[162:163], v[162:163], v[22:23]
	v_pk_mul_f32 v[164:165], v[164:165], s[54:55] op_sel_hi:[1,0]
	v_pk_mul_f32 v[166:167], v[166:167], s[54:55] op_sel_hi:[1,0]
	v_pk_mul_f32 v[164:165], v[164:165], v[24:25]
	v_pk_mul_f32 v[166:167], v[166:167], v[26:27]
	v_pk_mul_f32 v[168:169], v[168:169], s[54:55] op_sel_hi:[1,0]
	v_pk_mul_f32 v[170:171], v[170:171], s[54:55] op_sel_hi:[1,0]
	v_pk_mul_f32 v[168:169], v[168:169], v[28:29]
	v_pk_mul_f32 v[170:171], v[170:171], v[30:31]
	global_store_dwordx4 v132, v[140:143], s[40:41]
	global_store_dwordx4 v132, v[144:147], s[40:41] offset:1024
	global_store_dwordx4 v132, v[148:151], s[40:41] offset:2048
	global_store_dwordx4 v132, v[152:155], s[40:41] offset:3072
	global_store_dwordx4 v134, v[156:159], s[40:41]
	global_store_dwordx4 v134, v[160:163], s[40:41] offset:1024
	global_store_dwordx4 v134, v[164:167], s[40:41] offset:2048
	global_store_dwordx4 v134, v[168:171], s[40:41] offset:3072
	v_add_u32_e32 v132, 0x1000000, v132
	v_add_u32_e32 v134, 0x1000000, v134
	v_add_u32_e32 v136, 0x1000000, v136
	v_add_u32_e32 v137, 0x1000000, v137
	global_load_dwordx4 v[140:143], v136, s[40:41]
	global_load_dwordx4 v[144:147], v136, s[40:41] offset:1024
	global_load_dwordx4 v[148:151], v136, s[40:41] offset:2048
	global_load_dwordx4 v[152:155], v136, s[40:41] offset:3072
	global_load_dwordx4 v[156:159], v137, s[40:41]
	global_load_dwordx4 v[160:163], v137, s[40:41] offset:1024
	global_load_dwordx4 v[164:167], v137, s[40:41] offset:2048
	global_load_dwordx4 v[168:171], v137, s[40:41] offset:3072
	s_waitcnt vmcnt(16)
; #define FIN_LOAD(V, R_) { const float* s = p->out + (size_t)(R_) * DM; UFOR(j, 8) V[j] = *(const float4*)(s + j * 256 + lane * 4); }
; __device__ __forceinline__ void phase_final(KP p) {
;     ...
;   int r = bid_ * 8 + wv;
;   if (r < ML) FIN_LOAD(va, r);
;   for (; r < ML; r += 2 * stride) {
;     if (r + stride < ML) FIN_LOAD(vb, r + stride);
;     FIN_BODY(va, r);
;     if (r + 2 * stride < ML) FIN_LOAD(va, r + 2 * stride);
;     if (r + stride < ML) FIN_BODY(vb, r + stride);
;   }
	v_pk_mul_f32 v[128:129], v[96:97], v[96:97]
	v_pk_fma_f32 v[128:129], v[98:99], v[98:99], v[128:129]
	v_pk_fma_f32 v[128:129], v[100:101], v[100:101], v[128:129]
	v_pk_fma_f32 v[128:129], v[102:103], v[102:103], v[128:129]
	v_pk_fma_f32 v[128:129], v[104:105], v[104:105], v[128:129]
	v_pk_fma_f32 v[128:129], v[106:107], v[106:107], v[128:129]
	v_pk_fma_f32 v[128:129], v[108:109], v[108:109], v[128:129]
	v_pk_fma_f32 v[128:129], v[110:111], v[110:111], v[128:129]
	v_pk_fma_f32 v[128:129], v[112:113], v[112:113], v[128:129]
	v_pk_fma_f32 v[128:129], v[114:115], v[114:115], v[128:129]
	v_pk_fma_f32 v[128:129], v[116:117], v[116:117], v[128:129]
	v_pk_fma_f32 v[128:129], v[118:119], v[118:119], v[128:129]
	v_pk_fma_f32 v[128:129], v[120:121], v[120:121], v[128:129]
	v_pk_fma_f32 v[128:129], v[122:123], v[122:123], v[128:129]
	v_pk_fma_f32 v[128:129], v[124:125], v[124:125], v[128:129]
	v_pk_fma_f32 v[128:129], v[126:127], v[126:127], v[128:129]
	v_add_f32_e32 v130, v128, v129
	s_nop 1
	v_add_f32_dpp v130, v130, v130 quad_perm:[1,0,3,2] row_mask:0xf bank_mask:0xf bound_ctrl:1
	s_nop 1
	v_add_f32_dpp v130, v130, v130 quad_perm:[2,3,0,1] row_mask:0xf bank_mask:0xf bound_ctrl:1
	s_nop 1
	v_add_f32_dpp v130, v130, v130 row_half_mirror row_mask:0xf bank_mask:0xf bound_ctrl:1
	s_nop 1
	v_add_f32_dpp v130, v130, v130 row_mirror row_mask:0xf bank_mask:0xf bound_ctrl:1
	s_nop 0
	v_readlane_b32 s14, v130, 0
	v_readlane_b32 s15, v130, 16
	v_readlane_b32 s6, v130, 32
	v_readlane_b32 s19, v130, 48
	s_nop 0
	v_mov_b32_e32 v128, s15
	v_add_f32_e32 v128, s14, v128
	v_mov_b32_e32 v129, s19
	v_add_f32_e32 v129, s6, v129
	v_add_f32_e32 v128, v128, v129
	v_mov_b32_e32 v129, 0x358637bd
	v_fmamk_f32 v128, v128, 0x3a000000, v129
	v_rsq_f32_e32 v128, v128
	s_nop 0
	v_readfirstlane_b32 s54, v128
	s_nop 1
	v_pk_mul_f32 v[96:97], v[96:97], s[54:55] op_sel_hi:[1,0]
	v_pk_mul_f32 v[98:99], v[98:99], s[54:55] op_sel_hi:[1,0]
	v_pk_mul_f32 v[96:97], v[96:97], v[0:1]
	v_pk_mul_f32 v[98:99], v[98:99], v[2:3]
	v_pk_mul_f32 v[100:101], v[100:101], s[54:55] op_sel_hi:[1,0]
	v_pk_mul_f32 v[102:103], v[102:103], s[54:55] op_sel_hi:[1,0]
	v_pk_mul_f32 v[100:101], v[100:101], v[4:5]
	v_pk_mul_f32 v[102:103], v[102:103], v[6:7]
	v_pk_mul_f32 v[104:105], v[104:105], s[54:55] op_sel_hi:[1,0]
	v_pk_mul_f32 v[106:107], v[106:107], s[54:55] op_sel_hi:[1,0]
	v_pk_mul_f32 v[104:105], v[104:105], v[8:9]
	v_pk_mul_f32 v[106:107], v[106:107], v[10:11]
	v_pk_mul_f32 v[108:109], v[108:109], s[54:55] op_sel_hi:[1,0]
	v_pk_mul_f32 v[110:111], v[110:111], s[54:55] op_sel_hi:[1,0]
	v_pk_mul_f32 v[108:109], v[108:109], v[12:13]
	v_pk_mul_f32 v[110:111], v[110:111], v[14:15]
	v_pk_mul_f32 v[112:113], v[112:113], s[54:55] op_sel_hi:[1,0]
	v_pk_mul_f32 v[114:115], v[114:115], s[54:55] op_sel_hi:[1,0]
	v_pk_mul_f32 v[112:113], v[112:113], v[16:17]
	v_pk_mul_f32 v[114:115], v[114:115], v[18:19]
	v_pk_mul_f32 v[116:117], v[116:117], s[54:55] op_sel_hi:[1,0]
	v_pk_mul_f32 v[118:119], v[118:119], s[54:55] op_sel_hi:[1,0]
	v_pk_mul_f32 v[116:117], v[116:117], v[20:21]
	v_pk_mul_f32 v[118:119], v[118:119], v[22:23]
	v_pk_mul_f32 v[120:121], v[120:121], s[54:55] op_sel_hi:[1,0]
	v_pk_mul_f32 v[122:123], v[122:123], s[54:55] op_sel_hi:[1,0]
	v_pk_mul_f32 v[120:121], v[120:121], v[24:25]
	v_pk_mul_f32 v[122:123], v[122:123], v[26:27]
	v_pk_mul_f32 v[124:125], v[124:125], s[54:55] op_sel_hi:[1,0]
	v_pk_mul_f32 v[126:127], v[126:127], s[54:55] op_sel_hi:[1,0]
	v_pk_mul_f32 v[124:125], v[124:125], v[28:29]
	v_pk_mul_f32 v[126:127], v[126:127], v[30:31]
	global_store_dwordx4 v132, v[96:99], s[40:41]
	global_store_dwordx4 v132, v[100:103], s[40:41] offset:1024
	global_store_dwordx4 v132, v[104:107], s[40:41] offset:2048
	global_store_dwordx4 v132, v[108:111], s[40:41] offset:3072
	global_store_dwordx4 v134, v[112:115], s[40:41]
	global_store_dwordx4 v134, v[116:119], s[40:41] offset:1024
	global_store_dwordx4 v134, v[120:123], s[40:41] offset:2048
	global_store_dwordx4 v134, v[124:127], s[40:41] offset:3072
	v_add_u32_e32 v132, 0x1000000, v132
	v_add_u32_e32 v134, 0x1000000, v134
	s_cmp_eq_u32 s7, 1
	s_cbranch_scc1 .Lfinal_nopf
	v_add_u32_e32 v136, 0x1000000, v136
	v_add_u32_e32 v137, 0x1000000, v137
	global_load_dwordx4 v[96:99], v136, s[40:41]
	global_load_dwordx4 v[100:103], v136, s[40:41] offset:1024
	global_load_dwordx4 v[104:107], v136, s[40:41] offset:2048
	global_load_dwordx4 v[108:111], v136, s[40:41] offset:3072
	global_load_dwordx4 v[112:115], v137, s[40:41]
	global_load_dwordx4 v[116:119], v137, s[40:41] offset:1024
	global_load_dwordx4 v[120:123], v137, s[40:41] offset:2048
	global_load_dwordx4 v[124:127], v137, s[40:41] offset:3072
; #define FIN_LOAD(V, R_) { const float* s = p->out + (size_t)(R_) * DM; UFOR(j, 8) V[j] = *(const float4*)(s + j * 256 + lane * 4); }
; __device__ __forceinline__ void phase_final(KP p) {
;     ...
;   int r = bid_ * 8 + wv;
;   if (r < ML) FIN_LOAD(va, r);
;   for (; r < ML; r += 2 * stride) {
;     if (r + stride < ML) FIN_LOAD(vb, r + stride);
;     FIN_BODY(va, r);
;     if (r + 2 * stride < ML) FIN_LOAD(va, r + 2 * stride);
;     if (r + stride < ML) FIN_BODY(vb, r + stride);
;   }
.Lfinal_nopf:
	s_waitcnt vmcnt(8)
	v_pk_mul_f32 v[128:129], v[140:141], v[140:141]
	v_pk_fma_f32 v[128:129], v[142:143], v[142:143], v[128:129]
	v_pk_fma_f32 v[128:129], v[144:145], v[144:145], v[128:129]
	v_pk_fma_f32 v[128:129], v[146:147], v[146:147], v[128:129]
	v_pk_fma_f32 v[128:129], v[148:149], v[148:149], v[128:129]
	v_pk_fma_f32 v[128:129], v[150:151], v[150:151], v[128:129]
	v_pk_fma_f32 v[128:129], v[152:153], v[152:153], v[128:129]
	v_pk_fma_f32 v[128:129], v[154:155], v[154:155], v[128:129]
	v_pk_fma_f32 v[128:129], v[156:157], v[156:157], v[128:129]
	v_pk_fma_f32 v[128:129], v[158:159], v[158:159], v[128:129]
	v_pk_fma_f32 v[128:129], v[160:161], v[160:161], v[128:129]
	v_pk_fma_f32 v[128:129], v[162:163], v[162:163], v[128:129]
	v_pk_fma_f32 v[128:129], v[164:165], v[164:165], v[128:129]
	v_pk_fma_f32 v[128:129], v[166:167], v[166:167], v[128:129]
	v_pk_fma_f32 v[128:129], v[168:169], v[168:169], v[128:129]
	v_pk_fma_f32 v[128:129], v[170:171], v[170:171], v[128:129]
	v_add_f32_e32 v130, v128, v129
	s_nop 1
	v_add_f32_dpp v130, v130, v130 quad_perm:[1,0,3,2] row_mask:0xf bank_mask:0xf bound_ctrl:1
	s_nop 1
	v_add_f32_dpp v130, v130, v130 quad_perm:[2,3,0,1] row_mask:0xf bank_mask:0xf bound_ctrl:1
	s_nop 1
	v_add_f32_dpp v130, v130, v130 row_half_mirror row_mask:0xf bank_mask:0xf bound_ctrl:1
	s_nop 1
	v_add_f32_dpp v130, v130, v130 row_mirror row_mask:0xf bank_mask:0xf bound_ctrl:1
	s_nop 0
	v_readlane_b32 s14, v130, 0
	v_readlane_b32 s15, v130, 16
	v_readlane_b32 s6, v130, 32
	v_readlane_b32 s19, v130, 48
	s_nop 0
	v_mov_b32_e32 v128, s15
	v_add_f32_e32 v128, s14, v128
	v_mov_b32_e32 v129, s19
	v_add_f32_e32 v129, s6, v129
	v_add_f32_e32 v128, v128, v129
	v_mov_b32_e32 v129, 0x358637bd
	v_fmamk_f32 v128, v128, 0x3a000000, v129
	v_rsq_f32_e32 v128, v128
	s_nop 0
	v_readfirstlane_b32 s54, v128
	s_nop 1
	v_pk_mul_f32 v[140:141], v[140:141], s[54:55] op_sel_hi:[1,0]
	v_pk_mul_f32 v[142:143], v[142:143], s[54:55] op_sel_hi:[1,0]
	v_pk_mul_f32 v[140:141], v[140:141], v[0:1]
	v_pk_mul_f32 v[142:143], v[142:143], v[2:3]
	v_pk_mul_f32 v[144:145], v[144:145], s[54:55] op_sel_hi:[1,0]
	v_pk_mul_f32 v[146:147], v[146:147], s[54:55] op_sel_hi:[1,0]
	v_pk_mul_f32 v[144:145], v[144:145], v[4:5]
	v_pk_mul_f32 v[146:147], v[146:147], v[6:7]
	v_pk_mul_f32 v[148:149], v[148:149], s[54:55] op_sel_hi:[1,0]
	v_pk_mul_f32 v[150:151], v[150:151], s[54:55] op_sel_hi:[1,0]
	v_pk_mul_f32 v[148:149], v[148:149], v[8:9]
	v_pk_mul_f32 v[150:151], v[150:151], v[10:11]
	v_pk_mul_f32 v[152:153], v[152:153], s[54:55] op_sel_hi:[1,0]
	v_pk_mul_f32 v[154:155], v[154:155], s[54:55] op_sel_hi:[1,0]
	v_pk_mul_f32 v[152:153], v[152:153], v[12:13]
	v_pk_mul_f32 v[154:155], v[154:155], v[14:15]
	v_pk_mul_f32 v[156:157], v[156:157], s[54:55] op_sel_hi:[1,0]
	v_pk_mul_f32 v[158:159], v[158:159], s[54:55] op_sel_hi:[1,0]
	v_pk_mul_f32 v[156:157], v[156:157], v[16:17]
	v_pk_mul_f32 v[158:159], v[158:159], v[18:19]
	v_pk_mul_f32 v[160:161], v[160:161], s[54:55] op_sel_hi:[1,0]
	v_pk_mul_f32 v[162:163], v[162:163], s[54:55] op_sel_hi:[1,0]
	v_pk_mul_f32 v[160:161], v[160:161], v[20:21]
	v_pk_mul_f32 v[162:163], v[162:163], v[22:23]
	v_pk_mul_f32 v[164:165], v[164:165], s[54:55] op_sel_hi:[1,0]
	v_pk_mul_f32 v[166:167], v[166:167], s[54:55] op_sel_hi:[1,0]
	v_pk_mul_f32 v[164:165], v[164:165], v[24:25]
	v_pk_mul_f32 v[166:167], v[166:167], v[26:27]
	v_pk_mul_f32 v[168:169], v[168:169], s[54:55] op_sel_hi:[1,0]
	v_pk_mul_f32 v[170:171], v[170:171], s[54:55] op_sel_hi:[1,0]
	v_pk_mul_f32 v[168:169], v[168:169], v[28:29]
	v_pk_mul_f32 v[170:171], v[170:171], v[30:31]
	global_store_dwordx4 v132, v[140:143], s[40:41]
	global_store_dwordx4 v132, v[144:147], s[40:41] offset:1024
	global_store_dwordx4 v132, v[148:151], s[40:41] offset:2048
	global_store_dwordx4 v132, v[152:155], s[40:41] offset:3072
	global_store_dwordx4 v134, v[156:159], s[40:41]
	global_store_dwordx4 v134, v[160:163], s[40:41] offset:1024
	global_store_dwordx4 v134, v[164:167], s[40:41] offset:2048
	global_store_dwordx4 v134, v[168:171], s[40:41] offset:3072
	v_add_u32_e32 v132, 0x1000000, v132
	v_add_u32_e32 v134, 0x1000000, v134
	s_add_i32 s7, s7, 1
	s_cmp_lt_u32 s7, 2
	s_cbranch_scc1 .Lfinal_block
	s_branch .LBB0_1266
	s_mov_b32 s10, 0x8000
	s_waitcnt vmcnt(5)
	v_ashrrev_i32_e32 v0, 6, v135
	v_lshl_add_u32 v90, s78, 3, v0
	v_cmp_gt_i32_e32 vcc, s10, v90
	s_mov_b32 s8, 0
	s_and_saveexec_b64 s[4:5], vcc
	v_readlane_b32 s16, v253, 2
	s_cbranch_execz .LBB0_1265
	s_load_dwordx4 s[40:43], s[0:1], s8 offset:0xd0
	v_ashrrev_i32_e32 v91, 31, v90
	v_lshlrev_b32_e32 v2, 2, v135
	v_lshlrev_b64 v[0:1], 13, v[90:91]
	s_waitcnt vmcnt(1)
	v_and_b32_e32 v64, 0xfc, v2
	s_waitcnt lgkmcnt(0)
	v_lshl_add_u64 v[0:1], s[42:43], 0, v[0:1]
	v_mov_b32_e32 v67, 0
	v_lshlrev_b32_e32 v66, 2, v64
	v_lshl_add_u64 v[16:17], v[0:1], 0, v[66:67]
	s_movk_i32 s11, 0x1000
	s_waitcnt vmcnt(0)
	v_add_co_u32_e32 v28, vcc, s11, v16
	global_load_dwordx4 v[0:3], v[16:17], off
	global_load_dwordx4 v[4:7], v[16:17], off offset:1024
	global_load_dwordx4 v[8:11], v[16:17], off offset:2048
	global_load_dwordx4 v[12:15], v[16:17], off offset:3072
	v_addc_co_u32_e32 v29, vcc, 0, v17, vcc
	global_load_dwordx4 v[16:19], v[28:29], off
	global_load_dwordx4 v[20:23], v[28:29], off offset:1024
	global_load_dwordx4 v[24:27], v[28:29], off offset:2048
	global_load_dwordx4 v[36:39], v[28:29], off offset:3072
	v_or_b32_e32 v28, 0x400, v64
	v_lshl_add_u64 v[68:69], s[42:43], 0, v[66:67]
	v_lshl_add_u64 v[70:71], s[40:41], 0, v[66:67]
	v_lshlrev_b32_e32 v66, 2, v28
	v_or_b32_e32 v30, 0x500, v64
	v_lshl_add_u64 v[72:73], s[40:41], 0, v[66:67]
	v_lshlrev_b32_e32 v66, 2, v30
	v_or_b32_e32 v32, 0x600, v64
	v_lshl_add_u64 v[74:75], s[40:41], 0, v[66:67]
	v_lshlrev_b32_e32 v66, 2, v32
	v_or_b32_e32 v34, 0x700, v64
	v_lshl_add_u64 v[76:77], s[40:41], 0, v[66:67]
	v_lshlrev_b32_e32 v66, 2, v34
	v_lshl_add_u64 v[78:79], s[40:41], 0, v[66:67]
	s_mov_b64 s[6:7], 0
	v_mov_b32_e32 v65, 0x358637bd
	s_mov_b32 s12, 0x800000
	v_lshlrev_b32_e32 v80, 2, v28
	v_lshlrev_b32_e32 v82, 2, v30
	v_lshlrev_b32_e32 v84, 2, v32
	v_lshlrev_b32_e32 v86, 2, v34
	s_movk_i32 s13, 0x7fff
	s_branch .LBB0_1259
